# v62 + same s_setprio hand-off in scan step 2 (waves 4-7 lead at prio 1 until the kk=2 pack)
# speedup vs baseline: 1.0077x; 1.0048x over previous
.LBB0_380:
	s_or_b64 exec, exec, s[94:95]
	s_add_i32 s14, s15, 1
	s_cmp_lt_u32 s14, s0
	s_cselect_b32 s15, s14, s15
	s_lshl_b32 s16, s15, 6
	s_add_i32 s16, s16, s97
	s_cmp_eq_u32 s15, 0
	s_cselect_b32 s15, 0, 0x1000
	s_waitcnt lgkmcnt(0)
	s_barrier
	s_cmp_lg_u64 s[6:7], 0
	s_cbranch_scc0 .Lprio2_a
	s_setprio 1
.Lprio2_a:
	s_waitcnt vmcnt(0)
	ds_write_b128 v230, v[136:139]
	ds_write_b128 v230, v[140:143] offset:128
	ds_write_b128 v230, v[144:147] offset:256
	ds_write_b128 v230, v[148:151] offset:384
	v_readlane_b32 s98, v254, 52
	v_readlane_b32 s99, v254, 53
	v_readfirstlane_b32 s100, v1
	s_nop 3
	v_subrev_u32_e32 v151, s98, v176
	s_cmp_lg_u32 s100, 0
	s_cselect_b32 s101, 0x1000, s15
	s_add_i32 s100, s100, s16
	s_lshl_b32 s100, s100, 13
	s_add_u32 s98, s98, s100
	s_addc_u32 s99, s99, 0
	s_mul_i32 s100, s101, 6
	s_sub_u32 s98, s98, s100
	s_subb_u32 s99, s99, 0
	s_lshl_b32 s100, s101, 1
	v_add_u32_e32 v2, s16, v159
	v_ashrrev_i32_e32 v3, 31, v2
	v_lshlrev_b64 v[2:3], 7, v[2:3]
	v_lshl_add_u64 v[2:3], s[90:91], 0, v[2:3]
	global_load_dword v153, v[2:3], off
	ds_read_b128 v[84:87], v180
	ds_read_b128 v[88:91], v181 offset:17408
	ds_read_b128 v[92:95], v181 offset:21760
	global_load_dword v250, v151, s[98:99]
	ds_read_b128 v[68:71], v180 offset:64
	ds_read_b128 v[96:99], v181 offset:17472
	ds_read_b128 v[100:103], v181 offset:21824
	ds_read_b128 v[72:75], v180 offset:128
	ds_read_b128 v[76:79], v181 offset:17536
	v_add_u32_e32 v192, v178, v228
	ds_read_b128 v[80:83], v181 offset:21888
	ds_read_b128 v[104:107], v180 offset:192
	s_waitcnt lgkmcnt(8)
	v_mfma_f32_16x16x32_bf16 v[88:91], v[84:87], v[88:91], 0
	s_add_u32 s98, s98, s100
	s_addc_u32 s99, s99, 0
	global_load_dword v251, v151, s[98:99]
	ds_read_b128 v[108:111], v181 offset:17600
	s_waitcnt lgkmcnt(8)
	v_mfma_f32_16x16x32_bf16 v[84:87], v[84:87], v[92:95], 0
	ds_read_b128 v[112:115], v181 offset:21952
	s_waitcnt lgkmcnt(7)
	v_mfma_f32_16x16x32_bf16 v[88:91], v[68:71], v[96:99], v[88:91]
	s_waitcnt lgkmcnt(6)
	v_mfma_f32_16x16x32_bf16 v[84:87], v[68:71], v[100:103], v[84:87]
	s_waitcnt lgkmcnt(4)
	v_mfma_f32_16x16x32_bf16 v[88:91], v[72:75], v[76:79], v[88:91]
	s_add_u32 s98, s98, s100
	s_addc_u32 s99, s99, 0
	global_load_dword v252, v151, s[98:99]
	s_waitcnt lgkmcnt(3)
	v_mfma_f32_16x16x32_bf16 v[84:87], v[72:75], v[80:83], v[84:87]
	s_waitcnt lgkmcnt(1)
	v_mfma_f32_16x16x32_bf16 v[88:91], v[104:107], v[108:111], v[88:91]
	s_waitcnt lgkmcnt(0)
	v_mfma_f32_16x16x32_bf16 v[84:87], v[104:107], v[112:115], v[84:87]
	s_nop 7
	ds_write2_b32 v202, v88, v84 offset1:16
	ds_write2_b32 v202, v89, v85 offset0:68 offset1:84
	ds_write2_b32 v202, v90, v86 offset0:136 offset1:152
	s_add_u32 s98, s98, s100
	s_addc_u32 s99, s99, 0
	global_load_dword v249, v151, s[98:99]
	ds_write2_b32 v202, v91, v87 offset0:204 offset1:220
	ds_read2_b64 v[92:95], v224 offset1:4
	ds_read2_b64 v[100:103], v225 offset1:4
	ds_read2_b64 v[108:111], v226 offset1:4
	ds_read2_b64 v[116:119], v227 offset1:4
	ds_read2_b64 v[124:127], v224 offset0:8 offset1:12
	ds_read2_b64 v[68:71], v225 offset0:8 offset1:12
	ds_read2_b64 v[72:75], v226 offset0:8 offset1:12
	ds_read2_b64 v[76:79], v227 offset0:8 offset1:12
	v_cvt_pk_bf16_f32 v84, v4, v5
	s_add_u32 s98, s98, 0x2000
	s_addc_u32 s99, s99, 0
	global_load_dword v248, v151, s[98:99]
	v_cvt_pk_bf16_f32 v85, v6, v7
	v_cvt_pk_bf16_f32 v86, v12, v13
	v_cvt_pk_bf16_f32 v87, v14, v15
	v_cvt_pk_bf16_f32 v88, v8, v9
	v_cvt_pk_bf16_f32 v89, v10, v11
	v_cvt_pk_bf16_f32 v90, v16, v17
	v_cvt_pk_bf16_f32 v91, v18, v19
	ds_read2_b64 v[80:83], v224 offset0:16 offset1:20
	s_waitcnt lgkmcnt(8)
	v_mfma_f32_16x16x32_bf16 v[96:99], v[92:95], v[84:87], 0
	s_add_u32 s98, s98, 0x2000
	s_addc_u32 s99, s99, 0
	global_load_dword v247, v151, s[98:99]
	v_mfma_f32_16x16x32_bf16 v[92:95], v[92:95], v[88:91], 0
	ds_read2_b64 v[128:131], v225 offset0:16 offset1:20
	s_waitcnt lgkmcnt(8)
	v_mfma_f32_16x16x32_bf16 v[104:107], v[100:103], v[84:87], 0
	v_mfma_f32_16x16x32_bf16 v[100:103], v[100:103], v[88:91], 0
	ds_read2_b64 v[132:135], v226 offset0:16 offset1:20
	s_waitcnt lgkmcnt(8)
	v_mfma_f32_16x16x32_bf16 v[112:115], v[108:111], v[84:87], 0
	v_mfma_f32_16x16x32_bf16 v[108:111], v[108:111], v[88:91], 0
	ds_read2_b64 v[136:139], v227 offset0:16 offset1:20
	s_add_u32 s98, s98, 0x2000
	s_addc_u32 s99, s99, 0
	global_load_dword v246, v151, s[98:99]
	s_waitcnt lgkmcnt(8)
	v_mfma_f32_16x16x32_bf16 v[84:87], v[116:119], v[84:87], 0
	v_mfma_f32_16x16x32_bf16 v[88:91], v[116:119], v[88:91], 0
	v_cvt_pk_bf16_f32 v116, v20, v21
	v_cvt_pk_bf16_f32 v117, v22, v23
	v_cvt_pk_bf16_f32 v118, v28, v29
	v_cvt_pk_bf16_f32 v119, v30, v31
	v_cvt_pk_bf16_f32 v120, v24, v25
	v_cvt_pk_bf16_f32 v121, v26, v27
	v_cvt_pk_bf16_f32 v122, v32, v33
	s_add_u32 s98, s98, 0x2000
	s_addc_u32 s99, s99, 0
	global_load_dword v245, v151, s[98:99]
	v_cvt_pk_bf16_f32 v123, v34, v35
	ds_read2_b64 v[140:143], v224 offset0:24 offset1:28
	s_waitcnt lgkmcnt(8)
	v_mfma_f32_16x16x32_bf16 v[96:99], v[124:127], v[116:119], v[96:99]
	v_mfma_f32_16x16x32_bf16 v[92:95], v[124:127], v[120:123], v[92:95]
	ds_read2_b64 v[144:147], v225 offset0:24 offset1:28
	s_waitcnt lgkmcnt(8)
	v_mfma_f32_16x16x32_bf16 v[104:107], v[68:71], v[116:119], v[104:107]
	v_mfma_f32_16x16x32_bf16 v[100:103], v[68:71], v[120:123], v[100:103]
	s_waitcnt lgkmcnt(7)
	s_add_u32 s98, s98, 0x2000
	s_addc_u32 s99, s99, 0
	global_load_dword v244, v151, s[98:99]
	v_mfma_f32_16x16x32_bf16 v[112:115], v[72:75], v[116:119], v[112:115]
	v_mfma_f32_16x16x32_bf16 v[108:111], v[72:75], v[120:123], v[108:111]
	s_waitcnt lgkmcnt(6)
	v_mfma_f32_16x16x32_bf16 v[84:87], v[76:79], v[116:119], v[84:87]
	s_setprio 0
	v_cvt_pk_bf16_f32 v116, v36, v37
	v_cvt_pk_bf16_f32 v117, v38, v39
	v_cvt_pk_bf16_f32 v118, v44, v45
	v_mfma_f32_16x16x32_bf16 v[88:91], v[76:79], v[120:123], v[88:91]
	v_cvt_pk_bf16_f32 v119, v46, v47
	v_cvt_pk_bf16_f32 v120, v40, v41
	s_add_u32 s98, s98, 0x2000
	s_addc_u32 s99, s99, 0
	global_load_dword v243, v151, s[98:99]
	v_cvt_pk_bf16_f32 v121, v42, v43
	v_cvt_pk_bf16_f32 v122, v48, v49
	v_cvt_pk_bf16_f32 v123, v50, v51
	s_waitcnt lgkmcnt(5)
	v_mfma_f32_16x16x32_bf16 v[96:99], v[80:83], v[116:119], v[96:99]
	v_mfma_f32_16x16x32_bf16 v[92:95], v[80:83], v[120:123], v[92:95]
	s_waitcnt lgkmcnt(4)
	v_mfma_f32_16x16x32_bf16 v[104:107], v[128:131], v[116:119], v[104:107]
	v_mfma_f32_16x16x32_bf16 v[100:103], v[128:131], v[120:123], v[100:103]
	s_waitcnt lgkmcnt(3)
	s_add_u32 s98, s98, 0x2000
	s_addc_u32 s99, s99, 0
	global_load_dword v242, v151, s[98:99]
	v_mfma_f32_16x16x32_bf16 v[112:115], v[132:135], v[116:119], v[112:115]
	v_mfma_f32_16x16x32_bf16 v[108:111], v[132:135], v[120:123], v[108:111]
	s_waitcnt lgkmcnt(2)
	v_mfma_f32_16x16x32_bf16 v[84:87], v[136:139], v[116:119], v[84:87]
	v_mfma_f32_16x16x32_bf16 v[116:119], v[136:139], v[120:123], v[88:91]
	s_nop 2
	v_cvt_pk_bf16_f32 v88, v52, v53
	v_cvt_pk_bf16_f32 v89, v54, v55
	v_cvt_pk_bf16_f32 v90, v60, v61
	v_cvt_pk_bf16_f32 v91, v62, v63
	s_add_u32 s98, s98, 0x2000
	s_addc_u32 s99, s99, 0
	global_load_dword v241, v151, s[98:99]
	v_cvt_pk_bf16_f32 v120, v56, v57
	v_cvt_pk_bf16_f32 v121, v58, v59
	v_cvt_pk_bf16_f32 v122, v64, v65
	v_cvt_pk_bf16_f32 v123, v66, v67
	s_waitcnt lgkmcnt(1)
	v_mfma_f32_16x16x32_bf16 v[128:131], v[140:143], v[88:91], v[96:99]
	v_mfma_f32_16x16x32_bf16 v[124:127], v[140:143], v[120:123], v[92:95]
	s_nop 2
	ds_read2_b64 v[92:95], v226 offset0:24 offset1:28
	s_nop 2
	s_add_u32 s98, s98, 0x2000
	s_addc_u32 s99, s99, 0
	global_load_dword v240, v151, s[98:99]
	s_waitcnt lgkmcnt(1)
	v_mfma_f32_16x16x32_bf16 v[104:107], v[144:147], v[88:91], v[104:107]
	v_mfma_f32_16x16x32_bf16 v[132:135], v[144:147], v[120:123], v[100:103]
	s_waitcnt lgkmcnt(0)
	v_mfma_f32_16x16x32_bf16 v[100:103], v[92:95], v[88:91], v[112:115]
	v_mfma_f32_16x16x32_bf16 v[96:99], v[92:95], v[120:123], v[108:111]
	ds_read2_b64 v[92:95], v227 offset0:24 offset1:28
	s_waitcnt lgkmcnt(0)
	v_mfma_f32_16x16x32_bf16 v[88:91], v[92:95], v[88:91], v[84:87]
	v_mfma_f32_16x16x32_bf16 v[92:95], v[92:95], v[120:123], v[116:119]
	s_add_u32 s98, s98, 0x2000
	s_addc_u32 s99, s99, 0
	global_load_dword v239, v151, s[98:99]
	v_add_u32_e32 v120, s33, v156
	s_nop 0
	ds_read_b128 v[84:87], v120
	ds_read_b128 v[68:71], v120 offset:64
	ds_read_b128 v[72:75], v120 offset:128
	s_nop 0
	s_waitcnt lgkmcnt(2)
	v_mul_f32_e32 v2, 0x3fb8aa3b, v84
	v_mul_f32_e32 v84, 0x3fb8aa3b, v86
	v_exp_f32_e32 v108, v84
	s_add_u32 s98, s98, 0x2000
	s_addc_u32 s99, s99, 0
	global_load_dword v238, v151, s[98:99]
	v_mul_f32_e32 v84, 0x3fb8aa3b, v87
	v_exp_f32_e32 v109, v84
	v_mul_f32_e32 v3, 0x3fb8aa3b, v85
	v_exp_f32_e32 v2, v2
	v_exp_f32_e32 v3, v3
	v_pk_mul_f32 v[86:87], v[130:131], v[108:109]
	v_pk_mul_f32 v[118:119], v[126:127], v[108:109]
	v_pk_mul_f32 v[84:85], v[128:129], v[2:3]
	v_pk_mul_f32 v[116:117], v[124:125], v[2:3]
	s_waitcnt lgkmcnt(1)
	s_add_u32 s98, s98, 0x2000
	s_addc_u32 s99, s99, 0
	global_load_dword v237, v151, s[98:99]
	v_mul_f32_e32 v2, 0x3fb8aa3b, v68
	v_mul_f32_e32 v108, 0x3fb8aa3b, v70
	v_mul_f32_e32 v3, 0x3fb8aa3b, v69
	v_exp_f32_e32 v112, v108
	v_mul_f32_e32 v108, 0x3fb8aa3b, v71
	v_exp_f32_e32 v2, v2
	v_exp_f32_e32 v3, v3
	v_exp_f32_e32 v113, v108
	v_pk_mul_f32 v[108:109], v[104:105], v[2:3]
	v_pk_mul_f32 v[110:111], v[106:107], v[112:113]
	s_add_u32 s98, s98, 0x2000
	s_addc_u32 s99, s99, 0
	global_load_dword v236, v151, s[98:99]
	v_pk_mul_f32 v[114:115], v[134:135], v[112:113]
	v_pk_mul_f32 v[112:113], v[132:133], v[2:3]
	s_waitcnt lgkmcnt(0)
	v_mul_f32_e32 v2, 0x3fb8aa3b, v72
	v_mul_f32_e32 v3, 0x3fb8aa3b, v73
	v_mul_f32_e32 v104, 0x3fb8aa3b, v74
	v_mul_f32_e32 v105, 0x3fb8aa3b, v75
	v_exp_f32_e32 v2, v2
	v_exp_f32_e32 v3, v3
	v_exp_f32_e32 v104, v104
	v_exp_f32_e32 v105, v105
	v_pk_mul_f32 v[100:101], v[100:101], v[2:3]
	v_pk_mul_f32 v[102:103], v[102:103], v[104:105]
	v_pk_mul_f32 v[106:107], v[98:99], v[104:105]
	v_pk_mul_f32 v[104:105], v[96:97], v[2:3]
	ds_read_b128 v[96:99], v120 offset:192
	s_waitcnt lgkmcnt(0)
	s_barrier
	s_cmp_lg_u64 s[6:7], 0
	s_cbranch_scc0 .Lprio35_a
	s_setprio 1
